# FoX hot loop: 16-lane running-max min-reduction via DPP instead of 4 LDS bpermute round trips
# speedup vs baseline: 1.1247x; 1.0032x over previous
.LBB0_989:
	s_add_i32 s28, s85, s70
	s_sub_i32 s29, s28, 32
	v_cmp_ge_u32_e32 vcc, s28, v160
	v_cmp_le_u32_e64 s[28:29], s29, v170
	s_and_b64 s[28:29], vcc, s[28:29]
	s_and_saveexec_b64 s[58:59], s[28:29]
	s_cbranch_execz .LBB0_995
	s_mulk_i32 s1, 0x2400
	v_add_u32_e32 v0, s1, v184
	ds_read_b128 v[76:79], v0
	ds_read_b128 v[144:147], v0 offset:64
	ds_read_b128 v[84:87], v0 offset:2304
	ds_read_b128 v[104:107], v0 offset:4608
	ds_read_b128 v[136:139], v0 offset:6912
	v_add_u32_e32 v97, s85, v102
	v_cmp_lt_u32_e64 s[28:29], s95, v97
	v_add_u32_e32 v96, 0xffffffb2, v97
	s_waitcnt lgkmcnt(4)
	v_mfma_f32_16x16x32_bf16 v[80:83], v[76:79], v[4:7], 0
	s_waitcnt lgkmcnt(3)
	v_mfma_f32_16x16x32_bf16 v[148:151], v[144:147], v[8:11], v[80:83]
	s_nop 5
	ds_read_b128 v[80:83], v0 offset:2368
	v_mfma_f32_16x16x32_bf16 v[76:79], v[76:79], v[12:15], 0
	s_waitcnt lgkmcnt(3)
	v_mfma_f32_16x16x32_bf16 v[88:91], v[84:87], v[4:7], 0
	v_mfma_f32_16x16x32_bf16 v[84:87], v[84:87], v[12:15], 0
	v_mfma_f32_16x16x32_bf16 v[76:79], v[144:147], v[16:19], v[76:79]
	s_waitcnt lgkmcnt(0)
	v_mfma_f32_16x16x32_bf16 v[144:147], v[80:83], v[8:11], v[88:91]
	v_mfma_f32_16x16x32_bf16 v[80:83], v[80:83], v[16:19], v[84:87]
	s_nop 2
	ds_read_b128 v[88:91], v0 offset:6976
	ds_read_b128 v[84:87], v0 offset:4672
	v_mfma_f32_16x16x32_bf16 v[108:111], v[104:107], v[4:7], 0
	v_mov_b32_e32 v0, s94
	v_mfma_f32_16x16x32_bf16 v[104:107], v[104:107], v[12:15], 0
	s_waitcnt lgkmcnt(0)
	v_mfma_f32_16x16x32_bf16 v[192:195], v[84:87], v[8:11], v[108:111]
	v_mfma_f32_16x16x32_bf16 v[84:87], v[84:87], v[16:19], v[104:107]
	s_nop 4
	v_cndmask_b32_e64 v104, v148, v0, s[28:29]
	v_add_u32_e32 v0, 0xffffff80, v97
	v_cmp_gt_u32_e64 s[30:31], s96, v0
	v_add_u32_e32 v0, 0xffffff81, v97
	v_cmp_gt_u32_e64 s[34:35], s96, v0
	v_add_u32_e32 v0, 0xffffff82, v97
	v_cmp_gt_u32_e64 s[36:37], s96, v0
	v_add_u32_e32 v0, 16, v97
	v_cmp_lt_u32_e64 s[38:39], s95, v0
	v_mov_b32_e32 v0, s94
	v_mfma_f32_16x16x32_bf16 v[140:143], v[136:139], v[4:7], 0
	v_cndmask_b32_e64 v109, v144, v0, s[38:39]
	v_add_u32_e32 v0, 0xffffff90, v97
	v_cmp_gt_u32_e64 s[40:41], s96, v0
	v_add_u32_e32 v0, 0xffffff91, v97
	v_cmp_gt_u32_e64 s[42:43], s96, v0
	v_add_u32_e32 v0, 0xffffff92, v97
	v_cmp_gt_u32_e64 s[44:45], s96, v0
	v_add_u32_e32 v0, 32, v97
	v_cmp_lt_u32_e64 s[46:47], s95, v0
	v_mov_b32_e32 v0, s94
	v_mfma_f32_16x16x32_bf16 v[136:139], v[136:139], v[12:15], 0
	v_cndmask_b32_e64 v125, v192, v0, s[46:47]
	v_add_u32_e32 v0, 0xffffffa0, v97
	v_cmp_gt_u32_e64 s[48:49], s96, v0
	v_mfma_f32_16x16x32_bf16 v[140:143], v[88:91], v[8:11], v[140:143]
	v_add_u32_e32 v0, 0xffffffa1, v97
	v_cmp_gt_u32_e64 s[50:51], s96, v0
	v_add_u32_e32 v0, 0xffffffa2, v97
	v_cmp_gt_u32_e64 s[52:53], s96, v0
	v_add_u32_e32 v0, 48, v97
	v_cmp_lt_u32_e32 vcc, s95, v0
	v_mov_b32_e32 v0, s94
	v_mfma_f32_16x16x32_bf16 v[88:91], v[88:91], v[16:19], v[136:139]
	v_cndmask_b32_e64 v105, v149, v122, s[30:31]
	v_cndmask_b32_e64 v106, v150, v122, s[34:35]
	v_cndmask_b32_e64 v107, v151, v122, s[36:37]
	v_cndmask_b32_e32 v137, v140, v0, vcc
	v_add_u32_e32 v0, 0xffffffb0, v97
	v_cmp_lt_u32_e32 vcc, s97, v0
	v_add_u32_e32 v0, 0xffffffb1, v97
	v_cndmask_b32_e64 v110, v145, v122, s[40:41]
	v_cndmask_b32_e32 v138, v122, v141, vcc
	v_cmp_lt_u32_e32 vcc, s97, v0
	v_cndmask_b32_e64 v111, v146, v122, s[42:43]
	v_cndmask_b32_e64 v123, v147, v122, s[44:45]
	v_cndmask_b32_e32 v0, v122, v142, vcc
	v_cmp_lt_u32_e32 vcc, s97, v96
	v_cndmask_b32_e64 v126, v193, v122, s[48:49]
	v_cndmask_b32_e64 v127, v194, v122, s[50:51]
	v_cndmask_b32_e32 v103, v122, v143, vcc
	v_cmp_lt_i32_e32 vcc, v238, v239
	v_cndmask_b32_e64 v136, v195, v122, s[52:53]
	s_nop 0
	v_cndmask_b32_e32 v96, v237, v238, vcc
	v_cmp_lt_i32_e32 vcc, v240, v239
	v_lshlrev_b32_e32 v139, 2, v96
	s_nop 0
	v_cndmask_b32_e32 v96, v237, v240, vcc
	v_lshlrev_b32_e32 v140, 2, v96
	v_max3_f32 v96, v104, s94, v105
	v_max3_f32 v96, v96, v106, v107
	v_max3_f32 v96, v96, v109, v110
	v_max3_f32 v96, v96, v111, v123
	v_max3_f32 v96, v96, v125, v126
	v_max3_f32 v96, v96, v127, v136
	v_max3_f32 v96, v96, v137, v138
	v_max3_f32 v96, v96, v0, v103
	v_mov_b32_e32 v108, v96
	s_nop 1
	v_permlane16_swap_b32 v108, v96
	s_waitcnt lgkmcnt(0)
	v_max_f32_e32 v96, v96, v108
	v_mov_b32_e32 v108, v96
	s_nop 1
	v_permlane32_swap_b32 v108, v96
	s_waitcnt lgkmcnt(0)
	v_max3_f32 v96, v2, v96, v108
	v_cmp_neq_f32_e32 vcc, s94, v96
	s_nop 1
	v_cndmask_b32_e32 v108, 0, v96, vcc
	v_cmp_gt_f32_e32 vcc, v96, v2
	s_cbranch_vccz .LBB0_992
	v_sub_f32_e32 v2, v2, v108
	v_exp_f32_e32 v2, v2
	s_nop 0
	v_pk_mul_f32 v[46:47], v[46:47], v[2:3] op_sel_hi:[1,0]
	v_pk_mul_f32 v[44:45], v[44:45], v[2:3] op_sel_hi:[1,0]
	v_pk_mul_f32 v[74:75], v[74:75], v[2:3] op_sel_hi:[1,0]
	v_pk_mul_f32 v[72:73], v[72:73], v[2:3] op_sel_hi:[1,0]
	v_pk_mul_f32 v[70:71], v[70:71], v[2:3] op_sel_hi:[1,0]
	v_pk_mul_f32 v[68:69], v[68:69], v[2:3] op_sel_hi:[1,0]
	v_pk_mul_f32 v[66:67], v[66:67], v[2:3] op_sel_hi:[1,0]
	v_pk_mul_f32 v[64:65], v[64:65], v[2:3] op_sel_hi:[1,0]
	v_pk_mul_f32 v[62:63], v[62:63], v[2:3] op_sel_hi:[1,0]
	v_pk_mul_f32 v[60:61], v[60:61], v[2:3] op_sel_hi:[1,0]
.LBB0_992:
	v_add_u32_e32 v141, -16, v97
	v_mov_b32_e32 v2, s94
	v_cmp_lt_u32_e32 vcc, s95, v141
	v_cndmask_b32_e64 v146, v81, v122, s[30:31]
	v_cndmask_b32_e64 v144, v82, v122, s[34:35]
	v_cndmask_b32_e32 v141, v76, v2, vcc
	v_add_u32_e32 v2, 0xffffff70, v97
	v_cmp_lt_u32_e32 vcc, s97, v2
	v_add_u32_e32 v2, 0xffffff71, v97
	v_cndmask_b32_e64 v142, v83, v122, s[36:37]
	v_cndmask_b32_e32 v143, v122, v77, vcc
	v_cmp_lt_u32_e32 vcc, s97, v2
	v_add_u32_e32 v2, 0xffffff72, v97
	v_max3_f32 v81, v141, s94, v143
	v_cndmask_b32_e32 v145, v122, v78, vcc
	v_cmp_lt_u32_e32 vcc, s97, v2
	v_mov_b32_e32 v2, s94
	v_cndmask_b32_e64 v148, v80, v2, s[28:29]
	v_cndmask_b32_e32 v147, v122, v79, vcc
	v_max3_f32 v81, v81, v145, v147
	v_max3_f32 v81, v81, v148, v146
	v_cndmask_b32_e64 v83, v84, v2, s[38:39]
	v_cndmask_b32_e64 v82, v85, v122, s[40:41]
	v_max3_f32 v81, v81, v144, v142
	v_cndmask_b32_e64 v80, v86, v122, s[42:43]
	v_cndmask_b32_e64 v79, v87, v122, s[44:45]
	v_max3_f32 v81, v81, v83, v82
	v_cndmask_b32_e64 v78, v88, v2, s[46:47]
	v_cndmask_b32_e64 v77, v89, v122, s[48:49]
	v_max3_f32 v81, v81, v80, v79
	v_cndmask_b32_e64 v76, v90, v122, s[50:51]
	v_cndmask_b32_e64 v2, v91, v122, s[52:53]
	v_max3_f32 v81, v81, v78, v77
	v_max3_f32 v81, v81, v76, v2
	v_mov_b32_e32 v84, v81
	s_nop 1
	v_permlane16_swap_b32 v84, v81
	s_waitcnt lgkmcnt(0)
	v_max_f32_e32 v81, v81, v84
	v_mov_b32_e32 v84, v81
	s_nop 1
	v_permlane32_swap_b32 v84, v81
	s_waitcnt lgkmcnt(0)
	v_max3_f32 v97, v3, v81, v84
	v_cmp_neq_f32_e32 vcc, s94, v97
	s_nop 1
	v_cndmask_b32_e32 v81, 0, v97, vcc
	v_cmp_gt_f32_e32 vcc, v97, v3
	s_cbranch_vccz .LBB0_994
	v_sub_f32_e32 v3, v3, v81
	v_exp_f32_e32 v84, v3
	s_nop 0
	v_pk_mul_f32 v[30:31], v[30:31], v[84:85] op_sel_hi:[1,0]
	v_pk_mul_f32 v[28:29], v[28:29], v[84:85] op_sel_hi:[1,0]
	v_pk_mul_f32 v[38:39], v[38:39], v[84:85] op_sel_hi:[1,0]
	v_pk_mul_f32 v[36:37], v[36:37], v[84:85] op_sel_hi:[1,0]
	v_pk_mul_f32 v[34:35], v[34:35], v[84:85] op_sel_hi:[1,0]
	v_pk_mul_f32 v[32:33], v[32:33], v[84:85] op_sel_hi:[1,0]
	v_pk_mul_f32 v[26:27], v[26:27], v[84:85] op_sel_hi:[1,0]
	v_pk_mul_f32 v[24:25], v[24:25], v[84:85] op_sel_hi:[1,0]
	v_pk_mul_f32 v[22:23], v[22:23], v[84:85] op_sel_hi:[1,0]
	v_pk_mul_f32 v[20:21], v[20:21], v[84:85] op_sel_hi:[1,0]

.LBB0_1060:
	v_sub_f32_e32 v97, v146, v123
	v_exp_f32_e32 v100, v97
	v_sub_f32_e32 v97, v147, v123
	v_exp_f32_e32 v101, v97
	v_sub_f32_e32 v97, v144, v123
	v_exp_f32_e32 v104, v97
	v_sub_f32_e32 v97, v145, v123
	v_sub_f32_e32 v3, v152, v123
	v_sub_f32_e32 v92, v153, v123
	v_exp_f32_e32 v105, v97
	v_sub_f32_e32 v97, v142, v123
	v_exp_f32_e32 v3, v3
	v_exp_f32_e32 v92, v92
	v_exp_f32_e32 v106, v97
	v_sub_f32_e32 v97, v143, v123
	v_sub_f32_e32 v84, v84, v2
	v_exp_f32_e32 v107, v97
	v_sub_f32_e32 v97, v140, v123
	v_exp_f32_e32 v103, v84
	v_sub_f32_e32 v84, v85, v2
	v_sub_f32_e32 v93, v150, v123
	v_sub_f32_e32 v94, v151, v123
	v_sub_f32_e32 v95, v148, v123
	v_sub_f32_e32 v96, v149, v123
	v_exp_f32_e32 v125, v97
	v_sub_f32_e32 v97, v141, v123
	v_exp_f32_e32 v141, v84
	v_sub_f32_e32 v84, v86, v2
	v_exp_f32_e32 v93, v93
	v_exp_f32_e32 v94, v94
	v_exp_f32_e32 v95, v95
	v_exp_f32_e32 v96, v96
	v_exp_f32_e32 v142, v84
	v_sub_f32_e32 v84, v87, v2
	s_mulk_i32 s37, 0x2300
	v_exp_f32_e32 v87, v84
	s_add_i32 s30, s30, s37
	v_cvt_pk_bf16_f32 v84, v3, v92
	v_lshlrev_b32_e32 v3, 1, v159
	v_sub_f32_e32 v88, v88, v2
	v_add3_u32 v3, s30, v183, v3
	v_exp_f32_e32 v140, v97
	v_exp_f32_e32 v97, v88
	v_sub_f32_e32 v88, v89, v2
	v_add_u32_e32 v143, 0x6800, v3
	v_exp_f32_e32 v98, v88
	v_sub_f32_e32 v88, v90, v2
	v_cvt_pk_bf16_f32 v85, v93, v94
	v_cvt_pk_bf16_f32 v86, v95, v96
	ds_read2_b64 v[92:95], v143 offset0:128 offset1:132
	v_exp_f32_e32 v99, v88
	v_sub_f32_e32 v88, v91, v2
	v_exp_f32_e32 v102, v88
	v_cvt_pk_bf16_f32 v96, v97, v98
	v_cvt_pk_bf16_f32 v98, v103, v141
	v_add_u32_e32 v141, 0x7000, v3
	v_cvt_pk_bf16_f32 v97, v99, v102
	v_cvt_pk_bf16_f32 v99, v142, v87
	v_cvt_pk_bf16_f32 v87, v100, v101
	ds_read2_b64 v[100:103], v141 offset0:160 offset1:164
	v_sub_f32_e32 v110, v110, v123
	v_sub_f32_e32 v111, v111, v123
	v_add_u32_e32 v123, 0x7800, v3
	s_waitcnt lgkmcnt(1)
	v_mfma_f32_16x16x32_bf16 v[68:71], v[92:95], v[84:87], v[68:71]
	v_add_u32_e32 v3, 0x8000, v3
	v_sub_f32_e32 v80, v80, v2
	s_mov_b32 s78, s76
	v_mfma_f32_16x16x32_bf16 v[52:55], v[92:95], v[96:99], v[52:55]
	ds_read2_b64 v[92:95], v123 offset0:192 offset1:196
	s_mov_b32 s79, s76
	v_exp_f32_e32 v142, v80
	s_waitcnt lgkmcnt(1)
	v_mfma_f32_16x16x32_bf16 v[64:67], v[100:103], v[84:87], v[64:67]
	v_sub_f32_e32 v80, v81, v2
	v_sub_f32_e32 v76, v76, v2
	s_mov_b32 s77, s76
	v_mfma_f32_16x16x32_bf16 v[48:51], v[100:103], v[96:99], v[48:51]
	ds_read2_b64 v[100:103], v3 offset0:224 offset1:228
	v_mov_b64_e32 v[90:91], s[78:79]
	v_exp_f32_e32 v144, v80
	s_waitcnt lgkmcnt(1)
	v_mfma_f32_16x16x32_bf16 v[56:59], v[92:95], v[84:87], v[56:59]
	v_sub_f32_e32 v80, v82, v2
	v_mov_b64_e32 v[88:89], s[76:77]
	v_exp_f32_e32 v145, v80
	v_mfma_f32_16x16x32_bf16 v[44:47], v[92:95], v[96:99], v[44:47]
	v_exp_f32_e32 v93, v76
	v_sub_f32_e32 v76, v77, v2
	v_sub_f32_e32 v80, v83, v2
	v_exp_f32_e32 v77, v76
	v_sub_f32_e32 v76, v78, v2
	v_sub_f32_e32 v2, v79, v2
	v_exp_f32_e32 v92, v80
	v_exp_f32_e32 v78, v76
	v_exp_f32_e32 v2, v2
	ds_read2_b64 v[80:83], v143 offset0:136 offset1:140
	s_waitcnt lgkmcnt(1)
	v_mfma_f32_16x16x32_bf16 v[60:63], v[100:103], v[84:87], v[60:63]
	v_exp_f32_e32 v110, v110
	v_exp_f32_e32 v111, v111
	v_cvt_pk_bf16_f32 v76, v104, v105
	v_mfma_f32_16x16x32_bf16 v[72:75], v[88:91], v[84:87], v[72:75]
	v_cvt_pk_bf16_f32 v85, v145, v92
	v_cvt_pk_bf16_f32 v87, v78, v2
	v_max_f32_e32 v2, v109, v109
	v_max_f32_e32 v92, v108, v108
	v_min_f32_e32 v2, v92, v2
	v_mfma_f32_16x16x32_bf16 v[40:43], v[88:91], v[96:99], v[40:43]
	v_cvt_pk_bf16_f32 v84, v142, v144
	v_cvt_pk_bf16_f32 v86, v93, v77
	v_cvt_pk_bf16_f32 v77, v106, v107
	v_mfma_f32_16x16x32_bf16 v[36:39], v[100:103], v[96:99], v[36:39]
	v_cvt_pk_bf16_f32 v78, v125, v140
	v_cvt_pk_bf16_f32 v79, v110, v111
	s_waitcnt lgkmcnt(0)
	v_mfma_f32_16x16x32_bf16 v[52:55], v[80:83], v[84:87], v[52:55]
	ds_read2_b64 v[92:95], v3 offset0:232 offset1:236
	v_min_f32_dpp v2, v2, v2 quad_perm:[1,0,3,2] row_mask:0xf bank_mask:0xf
	v_mfma_f32_16x16x32_bf16 v[68:71], v[80:83], v[76:79], v[68:71]
	ds_read2_b64 v[80:83], v141 offset0:168 offset1:172
	v_min_f32_dpp v2, v2, v2 quad_perm:[2,3,0,1] row_mask:0xf bank_mask:0xf
	s_waitcnt lgkmcnt(0)
	v_mfma_f32_16x16x32_bf16 v[64:67], v[80:83], v[76:79], v[64:67]
	s_nop 0
	v_min_f32_dpp v2, v2, v2 row_half_mirror row_mask:0xf bank_mask:0xf
	v_mfma_f32_16x16x32_bf16 v[48:51], v[80:83], v[84:87], v[48:51]
	ds_read2_b64 v[80:83], v123 offset0:200 offset1:204
	v_min_f32_dpp v2, v2, v2 row_mirror row_mask:0xf bank_mask:0xf
	v_mfma_f32_16x16x32_bf16 v[40:43], v[88:91], v[84:87], v[40:43]
	s_waitcnt lgkmcnt(0)
	v_mfma_f32_16x16x32_bf16 v[56:59], v[80:83], v[76:79], v[56:59]
	v_mfma_f32_16x16x32_bf16 v[44:47], v[80:83], v[84:87], v[44:47]
	v_mfma_f32_16x16x32_bf16 v[60:63], v[92:95], v[76:79], v[60:63]
	v_mfma_f32_16x16x32_bf16 v[36:39], v[92:95], v[84:87], v[36:39]
	v_mfma_f32_16x16x32_bf16 v[72:75], v[88:91], v[76:79], v[72:75]
	s_and_saveexec_b64 s[30:31], s[26:27]
	s_cbranch_execz .LBB0_1062
	s_xor_b32 s1, s1, 1
	s_waitcnt lgkmcnt(0)
	v_mov_b32_e32 v3, v2
	v_max_f32_e32 v2, v2, v2
	v_lshl_add_u32 v76, s1, 4, v173
	v_min_f32_e32 v2, v2, v3
	ds_write_b32 v76, v2 offset:56076
